# compressed-branch importance table: LDS float atomic ds_add_f32 instead of ds_read / wait / add / ds_write round trips (4 per step), same f32 adds in the same order
# speedup vs baseline: 1.0072x; 1.0057x over previous
; #define LAS __attribute__((address_space(3)))
; __device__ __forceinline__ float quad_xor1(float v) { return __int_as_float(__builtin_amdgcn_update_dpp(0, __float_as_int(v), 0xB1, 0xF, 0xF, false)); }
; __device__ __forceinline__ float quad_xor2(float v) { return __int_as_float(__builtin_amdgcn_update_dpp(0, __float_as_int(v), 0x4E, 0xF, 0xF, false)); }
; template <int MODE>
; __device__ __forceinline__ void step_fragb(const bf16x8 (&qf)[4], bf16x8 (&kf)[2][4], FragV& cur, const bf16_t* __restrict__ KF, const bf16_t* __restrict__ VF,
;                                            int pos0, int pnext, int lo, int hi, AState& st, int lane, LAS float* imp) {
;     const int kq = lane >> 4;
;     f32x4 sa[2] = {(f32x4){0.f, 0.f, 0.f, 0.f}, (f32x4){0.f, 0.f, 0.f, 0.f}};
; #pragma unroll
;     for (int T = 0; T < 2; ++T)
; #pragma unroll
;         for (int s2 = 0; s2 < 4; ++s2) sa[T] = __builtin_amdgcn_mfma_f32_16x16x32_bf16(kf[T][s2], qf[s2], sa[T], 0, 0, 0);
;     load_fk(kf, KF, pnext, lane);
;     float sc[8]; bool vd[8]; float mx = -1e30f;
; #pragma unroll
;     for (int T = 0; T < 2; ++T)
; #pragma unroll
;         for (int r = 0; r < 4; ++r) { const int p = pos0 + 16 * T + 4 * kq + r; const bool v = (p >= lo) & (p <= hi); const float x = sa[T][r] * SL2;
;             sc[4 * T + r] = x; vd[4 * T + r] = v; mx = v ? fmaxf(mx, x) : mx; }
;     float p[8];
;     if (MODE == 2) {
;         const int l16 = lane & 15;
; #pragma unroll
;         for (int j = 0; j < 8; ++j) p[j] = vd[j] ? __builtin_amdgcn_exp2f(sc[j] - st.m) * st.l : 0.f;
; #pragma unroll
;         for (int T = 0; T < 2; ++T) {
;             float x = 2.f * (p[4 * T] + p[4 * T + 1] + p[4 * T + 2]) + p[4 * T + 3], y = p[4 * T + 3];
;             x += quad_xor1(x); x += quad_xor2(x); y += quad_xor1(y); y += quad_xor2(y);
;             if ((l16 & 3) == 0) { const int a = (pos0 >> 2) + 4 * T + kq; LAS float* ip = imp + (l16 >> 2) * IMP_LD + a;
;                 ip[0] += x;
;                 asm volatile("s_waitcnt lgkmcnt(0)" ::: "memory");
;                 ip[1] += y; }
;             asm volatile("s_waitcnt lgkmcnt(0)" ::: "memory");
;         }
.LBB0_939:
	s_waitcnt vmcnt(3)
	v_mfma_f32_16x16x32_bf16 v[58:61], v[58:61], v[14:17], 0
	s_add_i32 s20, s12, 1
	s_cmp_lt_u32 s20, s42
	s_cselect_b32 s18, s20, s12
	v_mfma_f32_16x16x32_bf16 v[74:77], v[74:77], v[14:17], 0
	s_lshl_b32 s21, s18, 5
	v_lshl_add_u64 v[82:83], s[10:11], 0, v[0:1]
	s_lshr_b32 s50, s21, 4
	s_waitcnt vmcnt(2)
	v_mfma_f32_16x16x32_bf16 v[54:57], v[54:57], v[6:9], v[58:61]
	global_load_dwordx4 v[86:89], v0, s[10:11]
	global_load_dwordx4 v[90:93], v0, s[10:11] offset:1024
	global_load_dwordx4 v[94:97], v0, s[10:11] offset:2048
	global_load_dwordx4 v[98:101], v0, s[10:11] offset:3072
	s_lshl_b64 s[10:11], s[50:51], 12
	v_mfma_f32_16x16x32_bf16 v[70:73], v[70:73], v[6:9], v[74:77]
	v_or_b32_e32 v140, s19, v211
	s_cmp_gt_i32 s19, -1
	s_cselect_b64 s[14:15], -1, 0
	s_waitcnt vmcnt(5)
	v_mfma_f32_16x16x32_bf16 v[50:53], v[50:53], v[10:13], v[54:57]
	v_add_co_u32_e32 v74, vcc, 0x1000, v82
	v_cmp_lt_i32_e64 s[12:13], v140, v134
	v_mfma_f32_16x16x32_bf16 v[66:69], v[66:69], v[10:13], v[70:73]
	v_addc_co_u32_e32 v75, vcc, 0, v83, vcc
	v_lshl_add_u64 v[54:55], v[136:137], 0, s[10:11]
	s_waitcnt vmcnt(4)
	v_mfma_f32_16x16x32_bf16 v[114:117], v[78:81], v[2:5], v[50:53]
	v_add_co_u32_e32 v78, vcc, s78, v54
	global_load_dwordx4 v[106:109], v[74:75], off
	global_load_dwordx4 v[110:113], v[74:75], off offset:1024
	global_load_dwordx4 v[102:105], v[74:75], off offset:2048
	global_load_dwordx4 v[82:85], v[74:75], off offset:3072
	v_addc_co_u32_e32 v79, vcc, 0, v55, vcc
	v_mfma_f32_16x16x32_bf16 v[146:149], v[62:65], v[2:5], v[66:69]
	global_load_dwordx4 v[74:77], v[54:55], off
	global_load_dwordx4 v[70:73], v[54:55], off offset:1024
	s_nop 0
	global_load_dwordx4 v[66:69], v[54:55], off offset:2048
	global_load_dwordx4 v[62:65], v[54:55], off offset:3072
	global_load_dwordx4 v[58:61], v[78:79], off
	s_nop 0
	global_load_dwordx4 v[54:57], v[78:79], off offset:1024
	global_load_dwordx4 v[50:53], v[78:79], off offset:2048
	s_nop 0
	global_load_dwordx4 v[78:81], v[78:79], off offset:3072
	v_fma_f32 v141, v146, s79, -v143
	v_exp_f32_e32 v141, v141
	v_fma_f32 v145, v147, s79, -v143
	v_exp_f32_e32 v146, v145
	v_cmp_le_i32_e32 vcc, v140, v134
	v_cmp_lt_i32_e64 s[10:11], -2, v140
	v_mul_f32_e32 v141, v138, v141
	s_and_b64 vcc, s[14:15], vcc
	v_cndmask_b32_e32 v145, 0, v141, vcc
	v_mul_f32_e32 v141, v138, v146
	s_and_b64 vcc, s[10:11], s[12:13]
	v_cndmask_b32_e32 v146, 0, v141, vcc
	v_fma_f32 v141, v148, s79, -v143
	v_exp_f32_e32 v148, v141
	v_fma_f32 v141, v149, s79, -v143
	v_exp_f32_e32 v149, v141
	v_or_b32_e32 v147, 3, v140
	v_or_b32_e32 v150, 2, v140
	v_cmp_lt_i32_e32 vcc, -4, v140
	v_cmp_le_i32_e64 s[12:13], v147, v135
	v_cmp_lt_i32_e64 s[10:11], -3, v140
	v_cmp_le_i32_e64 s[14:15], v150, v134
	v_pk_mul_f32 v[148:149], v[138:139], v[148:149]
	s_and_b64 vcc, vcc, s[12:13]
	v_cndmask_b32_e32 v147, 0, v149, vcc
	s_and_b64 vcc, s[10:11], s[14:15]
	v_cndmask_b32_e32 v148, 0, v148, vcc
	v_add_f32_e32 v149, v145, v146
	v_add_f32_e32 v149, v148, v149
	v_fma_f32 v149, 2.0, v149, v147
	v_mov_b32_e32 v153, 0
	v_add_f32_dpp v150, v147, v147 quad_perm:[1,0,3,2] row_mask:0xf bank_mask:0xf bound_ctrl:1
	v_add_f32_dpp v152, v149, v149 quad_perm:[1,0,3,2] row_mask:0xf bank_mask:0xf bound_ctrl:1
	v_mov_b32_e32 v151, 0
	v_mov_b32_e32 v141, v140
	v_mov_b32_dpp v153, v152 quad_perm:[2,3,0,1] row_mask:0xf bank_mask:0xf
	v_mov_b32_dpp v151, v150 quad_perm:[2,3,0,1] row_mask:0xf bank_mask:0xf
	v_add_u32_e32 v149, s19, v212
	s_and_saveexec_b64 s[10:11], s[4:5]
	s_cbranch_execz .LBB0_941
	v_add_f32_e32 v152, v152, v153
	v_add_f32_e32 v150, v150, v151
	ds_add_f32 v149, v152 offset:9216
	ds_add_f32 v149, v150 offset:9220
.LBB0_941:
	s_or_b64 exec, exec, s[10:11]
	v_fma_f32 v114, v114, s79, -v143
	v_fma_f32 v115, v115, s79, -v143
	v_exp_f32_e32 v114, v114
	v_exp_f32_e32 v115, v115
	v_or_b32_e32 v150, 17, v141
	v_or_b32_e32 v151, 16, v140
	v_cmp_lt_i32_e32 vcc, s81, v141
	v_cmp_le_i32_e64 s[12:13], v150, v135
	v_fma_f32 v116, v116, s79, -v143
	v_fma_f32 v117, v117, s79, -v143
	v_cmp_lt_i32_e64 s[10:11], s80, v140
	v_cmp_le_i32_e64 s[14:15], v151, v134
	v_pk_mul_f32 v[150:151], v[138:139], v[114:115]
	s_and_b64 vcc, vcc, s[12:13]
	v_exp_f32_e32 v116, v116
	v_exp_f32_e32 v117, v117
	v_cndmask_b32_e32 v114, 0, v151, vcc
	s_and_b64 vcc, s[10:11], s[14:15]
	v_cndmask_b32_e32 v115, 0, v150, vcc
	v_or_b32_e32 v150, 19, v141
	v_or_b32_e32 v151, 18, v140
	v_cmp_lt_i32_e32 vcc, s83, v141
	v_cmp_le_i32_e64 s[12:13], v150, v135
	v_cmp_lt_i32_e64 s[10:11], s82, v140
	v_cmp_le_i32_e64 s[14:15], v151, v134
	v_pk_mul_f32 v[140:141], v[138:139], v[116:117]
	s_and_b64 vcc, vcc, s[12:13]
	v_cndmask_b32_e32 v116, 0, v141, vcc
	s_and_b64 vcc, s[10:11], s[14:15]
	v_cndmask_b32_e32 v117, 0, v140, vcc
	v_add_f32_e32 v140, v115, v114
	v_add_f32_e32 v140, v117, v140
	s_waitcnt lgkmcnt(0)
	v_fma_f32 v140, 2.0, v140, v116
	v_mov_b32_e32 v151, 0
	v_mov_b32_e32 v141, 0
	v_add_f32_dpp v150, v140, v140 quad_perm:[1,0,3,2] row_mask:0xf bank_mask:0xf bound_ctrl:1
	v_add_f32_dpp v140, v116, v116 quad_perm:[1,0,3,2] row_mask:0xf bank_mask:0xf bound_ctrl:1
	s_nop 0
	v_mov_b32_dpp v151, v150 quad_perm:[2,3,0,1] row_mask:0xf bank_mask:0xf
	v_mov_b32_dpp v141, v140 quad_perm:[2,3,0,1] row_mask:0xf bank_mask:0xf
	s_and_saveexec_b64 s[10:11], s[4:5]
	s_cbranch_execz .LBB0_943
	v_add_f32_e32 v150, v150, v151
	v_add_f32_e32 v140, v140, v141
	ds_add_f32 v149, v150 offset:9232
	ds_add_f32 v149, v140 offset:9236
